# full stack: LDS-prefetched FFN epilogue inputs, de-serialised spatial-gating loads, header wait sunk below zeroing, 64-bit zeroing moves
# speedup vs baseline: 1.0006x; 1.0006x over previous
.LBB0_146:
	s_ashr_i32 s11, s10, 31
	v_cmp_lt_i64_e32 vcc, s[12:13], v[140:141]
	s_lshl_b64 s[12:13], s[10:11], 20
	s_add_u32 s12, s80, s12
	s_addc_u32 s13, s81, s13
	s_and_b64 s[14:15], vcc, exec
	s_cselect_b32 s11, s13, s17
	s_cselect_b32 s41, s12, s16
	s_ashr_i32 s9, s8, 31
	s_lshl_b64 s[14:15], s[8:9], 20
	s_add_u32 s14, s22, s14
	s_addc_u32 s15, s23, s15
	s_and_b64 s[20:21], vcc, exec
	s_cselect_b32 s9, s15, s19
	s_cselect_b32 s44, s14, s18
	s_add_u32 s16, s16, 0x80080
	s_addc_u32 s17, s17, 0
	s_add_u32 s45, s18, 0x100
	v_mov_b32_e32 v0, 0
	s_addc_u32 s46, s19, 0
	s_mov_b32 s47, -2
	v_mov_b32_e32 v1, v0
	v_mov_b64_e32 v[2:3], 0
	v_mov_b64_e32 v[4:5], 0
	v_mov_b64_e32 v[6:7], 0
	v_mov_b64_e32 v[16:17], 0
	v_mov_b64_e32 v[18:19], 0
	v_mov_b64_e32 v[20:21], 0
	v_mov_b64_e32 v[22:23], 0
	v_mov_b64_e32 v[32:33], 0
	v_mov_b64_e32 v[34:35], 0
	v_mov_b64_e32 v[36:37], 0
	v_mov_b64_e32 v[38:39], 0
	v_mov_b64_e32 v[48:49], 0
	v_mov_b64_e32 v[50:51], 0
	v_mov_b64_e32 v[52:53], 0
	v_mov_b64_e32 v[54:55], 0
	v_mov_b64_e32 v[8:9], 0
	v_mov_b64_e32 v[10:11], 0
	v_mov_b64_e32 v[12:13], 0
	v_mov_b64_e32 v[14:15], 0
	v_mov_b64_e32 v[24:25], 0
	v_mov_b64_e32 v[26:27], 0
	v_mov_b64_e32 v[28:29], 0
	v_mov_b64_e32 v[30:31], 0
	v_mov_b64_e32 v[40:41], 0
	v_mov_b64_e32 v[42:43], 0
	v_mov_b64_e32 v[44:45], 0
	v_mov_b64_e32 v[46:47], 0
	v_mov_b64_e32 v[56:57], 0
	v_mov_b64_e32 v[58:59], 0
	v_mov_b64_e32 v[60:61], 0
	v_mov_b64_e32 v[62:63], 0
	v_mov_b64_e32 v[64:65], 0
	v_mov_b64_e32 v[66:67], 0
	v_mov_b64_e32 v[68:69], 0
	v_mov_b64_e32 v[70:71], 0
	v_mov_b64_e32 v[80:81], 0
	v_mov_b64_e32 v[82:83], 0
	v_mov_b64_e32 v[84:85], 0
	v_mov_b64_e32 v[86:87], 0
	v_mov_b64_e32 v[96:97], 0
	v_mov_b64_e32 v[98:99], 0
	v_mov_b64_e32 v[100:101], 0
	v_mov_b64_e32 v[102:103], 0
	v_mov_b64_e32 v[112:113], 0
	v_mov_b64_e32 v[114:115], 0
	v_mov_b64_e32 v[116:117], 0
	v_mov_b64_e32 v[118:119], 0
	v_mov_b64_e32 v[72:73], 0
	v_mov_b64_e32 v[74:75], 0
	v_mov_b64_e32 v[76:77], 0
	v_mov_b64_e32 v[78:79], 0
	v_mov_b64_e32 v[88:89], 0
	v_mov_b64_e32 v[90:91], 0
	v_mov_b64_e32 v[92:93], 0
	v_mov_b64_e32 v[94:95], 0
	v_mov_b64_e32 v[104:105], 0
	v_mov_b64_e32 v[106:107], 0
	v_mov_b64_e32 v[108:109], 0
	v_mov_b64_e32 v[110:111], 0
	v_mov_b64_e32 v[120:121], 0
	v_mov_b64_e32 v[122:123], 0
	v_mov_b64_e32 v[124:125], 0
	v_mov_b64_e32 v[126:127], 0
	v_xor_b32_e32 v220, 64, v165
	v_xor_b32_e32 v221, 64, v166
	v_xor_b32_e32 v234, 64, v167
	v_add_u32_e32 v235, 0x18000, v161
	v_xor_b32_e32 v236, 64, v235
	s_waitcnt vmcnt(0)
	s_cmpk_lt_u32 s3, 0x100
	s_cbranch_scc1 .Lst_in_s1
	s_barrier

.LBB0_282:
	s_ashr_i32 s11, s10, 31
	s_lshl_b64 s[16:17], s[10:11], 20
	s_add_u32 s16, s22, s16
	s_addc_u32 s17, s23, s17
	s_and_b64 s[6:7], s[6:7], exec
	s_cselect_b32 s1, s17, s19
	s_cselect_b32 s11, s16, s18
	s_add_u32 s6, s20, 0x180080
	s_addc_u32 s7, s21, 0
	s_add_u32 s43, s18, 0x100
	v_mov_b32_e32 v0, 0
	s_addc_u32 s44, s19, 0
	s_mov_b32 s45, -2
	s_waitcnt lgkmcnt(0)
	v_mov_b32_e32 v1, v0
	v_mov_b64_e32 v[2:3], 0
	v_mov_b64_e32 v[4:5], 0
	v_mov_b64_e32 v[6:7], 0
	v_mov_b64_e32 v[16:17], 0
	v_mov_b64_e32 v[18:19], 0
	v_mov_b64_e32 v[20:21], 0
	v_mov_b64_e32 v[22:23], 0
	v_mov_b64_e32 v[32:33], 0
	v_mov_b64_e32 v[34:35], 0
	v_mov_b64_e32 v[36:37], 0
	v_mov_b64_e32 v[38:39], 0
	v_mov_b64_e32 v[48:49], 0
	v_mov_b64_e32 v[50:51], 0
	v_mov_b64_e32 v[52:53], 0
	v_mov_b64_e32 v[54:55], 0
	v_mov_b64_e32 v[8:9], 0
	v_mov_b64_e32 v[10:11], 0
	v_mov_b64_e32 v[12:13], 0
	v_mov_b64_e32 v[14:15], 0
	v_mov_b64_e32 v[24:25], 0
	v_mov_b64_e32 v[26:27], 0
	v_mov_b64_e32 v[28:29], 0
	v_mov_b64_e32 v[30:31], 0
	v_mov_b64_e32 v[40:41], 0
	v_mov_b64_e32 v[42:43], 0
	v_mov_b64_e32 v[44:45], 0
	v_mov_b64_e32 v[46:47], 0
	v_mov_b64_e32 v[56:57], 0
	v_mov_b64_e32 v[58:59], 0
	v_mov_b64_e32 v[60:61], 0
	v_mov_b64_e32 v[62:63], 0
	v_mov_b64_e32 v[64:65], 0
	v_mov_b64_e32 v[66:67], 0
	v_mov_b64_e32 v[68:69], 0
	v_mov_b64_e32 v[70:71], 0
	v_mov_b64_e32 v[80:81], 0
	v_mov_b64_e32 v[82:83], 0
	v_mov_b64_e32 v[84:85], 0
	v_mov_b64_e32 v[86:87], 0
	v_mov_b64_e32 v[96:97], 0
	v_mov_b64_e32 v[98:99], 0
	v_mov_b64_e32 v[100:101], 0
	v_mov_b64_e32 v[102:103], 0
	v_mov_b64_e32 v[112:113], 0
	v_mov_b64_e32 v[114:115], 0
	v_mov_b64_e32 v[116:117], 0
	v_mov_b64_e32 v[118:119], 0
	v_mov_b64_e32 v[72:73], 0
	v_mov_b64_e32 v[74:75], 0
	v_mov_b64_e32 v[76:77], 0
	v_mov_b64_e32 v[78:79], 0
	v_mov_b64_e32 v[88:89], 0
	v_mov_b64_e32 v[90:91], 0
	v_mov_b64_e32 v[92:93], 0
	v_mov_b64_e32 v[94:95], 0
	v_mov_b64_e32 v[104:105], 0
	v_mov_b64_e32 v[106:107], 0
	v_mov_b64_e32 v[108:109], 0
	v_mov_b64_e32 v[110:111], 0
	v_mov_b64_e32 v[120:121], 0
	v_mov_b64_e32 v[122:123], 0
	v_mov_b64_e32 v[124:125], 0
	v_mov_b64_e32 v[126:127], 0
	v_xor_b32_e32 v150, 64, v146
	v_xor_b32_e32 v151, 64, v147
	v_xor_b32_e32 v216, 64, v148
	v_add_u32_e32 v217, 0x18000, v145
	v_xor_b32_e32 v220, 64, v217
	s_waitcnt vmcnt(0)
	s_cmpk_lt_u32 s3, 0x100
	s_cbranch_scc1 .Lst_in_s2
	s_barrier

.LBB0_362:
	s_ashr_i32 s31, s30, 31
	v_cmp_lt_i64_e32 vcc, s[10:11], v[176:177]
	s_lshl_b64 s[10:11], s[30:31], 20
	s_add_u32 s34, s80, s10
	s_addc_u32 s35, s81, s11
	s_and_b64 s[10:11], vcc, exec
	s_cselect_b32 s31, s35, s7
	s_cselect_b32 s33, s34, s6
	s_ashr_i32 s29, s28, 31
	s_lshl_b64 s[10:11], s[28:29], 19
	s_add_u32 s36, s40, s10
	s_addc_u32 s37, s41, s11
	s_and_b64 s[10:11], vcc, exec
	s_cselect_b32 s29, s37, s9
	s_cselect_b32 s62, s36, s8
	s_add_u32 s63, s8, 0x100
	v_mov_b32_e32 v0, 0
	s_addc_u32 s64, s9, 0
	s_mov_b32 s65, -2
	v_mov_b32_e32 v1, v0
	v_mov_b64_e32 v[2:3], 0
	v_mov_b64_e32 v[64:65], 0
	v_mov_b64_e32 v[66:67], 0
	v_mov_b64_e32 v[8:9], 0
	v_mov_b64_e32 v[10:11], 0
	v_mov_b64_e32 v[68:69], 0
	v_mov_b64_e32 v[70:71], 0
	v_mov_b64_e32 v[12:13], 0
	v_mov_b64_e32 v[14:15], 0
	v_mov_b64_e32 v[110:111], 0
	v_mov_b64_e32 v[112:113], 0
	v_mov_b64_e32 v[16:17], 0
	v_mov_b64_e32 v[18:19], 0
	v_mov_b64_e32 v[118:119], 0
	v_mov_b64_e32 v[120:121], 0
	v_mov_b64_e32 v[4:5], 0
	v_mov_b64_e32 v[6:7], 0
	v_mov_b64_e32 v[72:73], 0
	v_mov_b64_e32 v[74:75], 0
	v_mov_b64_e32 v[20:21], 0
	v_mov_b64_e32 v[22:23], 0
	v_mov_b64_e32 v[114:115], 0
	v_mov_b64_e32 v[116:117], 0
	v_mov_b64_e32 v[24:25], 0
	v_mov_b64_e32 v[26:27], 0
	v_mov_b64_e32 v[122:123], 0
	v_mov_b64_e32 v[124:125], 0
	v_mov_b64_e32 v[28:29], 0
	v_mov_b64_e32 v[30:31], 0
	v_mov_b64_e32 v[126:127], 0
	v_mov_b64_e32 v[128:129], 0
	v_mov_b64_e32 v[32:33], 0
	v_mov_b64_e32 v[34:35], 0
	v_mov_b64_e32 v[130:131], 0
	v_mov_b64_e32 v[132:133], 0
	v_mov_b64_e32 v[36:37], 0
	v_mov_b64_e32 v[38:39], 0
	v_mov_b64_e32 v[134:135], 0
	v_mov_b64_e32 v[136:137], 0
	v_mov_b64_e32 v[44:45], 0
	v_mov_b64_e32 v[46:47], 0
	v_mov_b64_e32 v[142:143], 0
	v_mov_b64_e32 v[144:145], 0
	v_mov_b64_e32 v[56:57], 0
	v_mov_b64_e32 v[58:59], 0
	v_mov_b64_e32 v[154:155], 0
	v_mov_b64_e32 v[156:157], 0
	v_mov_b64_e32 v[40:41], 0
	v_mov_b64_e32 v[42:43], 0
	v_mov_b64_e32 v[138:139], 0
	v_mov_b64_e32 v[140:141], 0
	v_mov_b64_e32 v[48:49], 0
	v_mov_b64_e32 v[50:51], 0
	v_mov_b64_e32 v[146:147], 0
	v_mov_b64_e32 v[148:149], 0
	v_mov_b64_e32 v[52:53], 0
	v_mov_b64_e32 v[54:55], 0
	v_mov_b64_e32 v[150:151], 0
	v_mov_b64_e32 v[152:153], 0
	v_mov_b64_e32 v[60:61], 0
	v_mov_b64_e32 v[62:63], 0
	v_mov_b64_e32 v[158:159], 0
	v_mov_b64_e32 v[160:161], 0
	v_xor_b32_e32 v216, 64, v231
	v_xor_b32_e32 v217, 64, v241
	v_xor_b32_e32 v244, 64, v242
	v_add_u32_e32 v245, 0x18000, v229
	v_xor_b32_e32 v246, 64, v245
	v_add_u32_e32 v247, 0x1c000, v229
	v_xor_b32_e32 v248, 64, v247
	s_waitcnt vmcnt(0)
	s_cmpk_lt_u32 s3, 0x100
	s_cbranch_scc1 .Lst_in_s3
	s_barrier

.LBB0_507:
	s_add_u32 s0, s0, 0x160080
	s_addc_u32 s1, s1, 0
	s_add_u32 s39, s16, 0x100
	v_mov_b32_e32 v0, 0
	s_addc_u32 s40, s17, 0
	s_mov_b32 s41, -2
	s_waitcnt lgkmcnt(0)
	v_mov_b32_e32 v1, v0
	v_mov_b64_e32 v[2:3], 0
	v_mov_b64_e32 v[4:5], 0
	v_mov_b64_e32 v[6:7], 0
	v_mov_b64_e32 v[16:17], 0
	v_mov_b64_e32 v[18:19], 0
	v_mov_b64_e32 v[20:21], 0
	v_mov_b64_e32 v[22:23], 0
	v_mov_b64_e32 v[32:33], 0
	v_mov_b64_e32 v[34:35], 0
	v_mov_b64_e32 v[36:37], 0
	v_mov_b64_e32 v[38:39], 0
	v_mov_b64_e32 v[48:49], 0
	v_mov_b64_e32 v[50:51], 0
	v_mov_b64_e32 v[52:53], 0
	v_mov_b64_e32 v[54:55], 0
	v_mov_b64_e32 v[8:9], 0
	v_mov_b64_e32 v[10:11], 0
	v_mov_b64_e32 v[12:13], 0
	v_mov_b64_e32 v[14:15], 0
	v_mov_b64_e32 v[24:25], 0
	v_mov_b64_e32 v[26:27], 0
	v_mov_b64_e32 v[28:29], 0
	v_mov_b64_e32 v[30:31], 0
	v_mov_b64_e32 v[40:41], 0
	v_mov_b64_e32 v[42:43], 0
	v_mov_b64_e32 v[44:45], 0
	v_mov_b64_e32 v[46:47], 0
	v_mov_b64_e32 v[56:57], 0
	v_mov_b64_e32 v[58:59], 0
	v_mov_b64_e32 v[60:61], 0
	v_mov_b64_e32 v[62:63], 0
	v_mov_b64_e32 v[64:65], 0
	v_mov_b64_e32 v[66:67], 0
	v_mov_b64_e32 v[68:69], 0
	v_mov_b64_e32 v[70:71], 0
	v_mov_b64_e32 v[80:81], 0
	v_mov_b64_e32 v[82:83], 0
	v_mov_b64_e32 v[84:85], 0
	v_mov_b64_e32 v[86:87], 0
	v_mov_b64_e32 v[96:97], 0
	v_mov_b64_e32 v[98:99], 0
	v_mov_b64_e32 v[100:101], 0
	v_mov_b64_e32 v[102:103], 0
	v_mov_b64_e32 v[112:113], 0
	v_mov_b64_e32 v[114:115], 0
	v_mov_b64_e32 v[116:117], 0
	v_mov_b64_e32 v[118:119], 0
	v_mov_b64_e32 v[72:73], 0
	v_mov_b64_e32 v[74:75], 0
	v_mov_b64_e32 v[76:77], 0
	v_mov_b64_e32 v[78:79], 0
	v_mov_b64_e32 v[88:89], 0
	v_mov_b64_e32 v[90:91], 0
	v_mov_b64_e32 v[92:93], 0
	v_mov_b64_e32 v[94:95], 0
	v_mov_b64_e32 v[104:105], 0
	v_mov_b64_e32 v[106:107], 0
	v_mov_b64_e32 v[108:109], 0
	v_mov_b64_e32 v[110:111], 0
	v_mov_b64_e32 v[120:121], 0
	v_mov_b64_e32 v[122:123], 0
	v_mov_b64_e32 v[124:125], 0
	v_mov_b64_e32 v[126:127], 0
	v_xor_b32_e32 v216, 64, v141
	v_xor_b32_e32 v217, 64, v142
	v_xor_b32_e32 v244, 64, v143
	v_add_u32_e32 v245, 0x18000, v140
	v_xor_b32_e32 v246, 64, v245
	s_waitcnt vmcnt(0)
	s_cmpk_lt_u32 s3, 0x100
	s_cbranch_scc1 .Lst_in_s4
	s_barrier

.LBB0_598:
	s_ashr_i32 s21, s20, 31
	v_cmp_lt_i64_e32 vcc, s[22:23], v[136:137]
	s_lshl_b64 s[22:23], s[20:21], 20
	s_add_u32 s22, s80, s22
	s_addc_u32 s23, s81, s23
	s_and_b64 s[24:25], vcc, exec
	s_cselect_b32 s1, s23, s27
	s_cselect_b32 s13, s22, s26
	s_ashr_i32 s19, s18, 31
	s_lshl_b64 s[24:25], s[18:19], 20
	s_add_u32 s24, s34, s24
	s_addc_u32 s25, s35, s25
	s_and_b64 s[30:31], vcc, exec
	s_cselect_b32 s19, s25, s29
	s_cselect_b32 s21, s24, s28
	s_add_u32 s26, s26, 0x80080
	s_addc_u32 s27, s27, 0
	s_add_u32 s33, s28, 0x100
	v_mov_b32_e32 v0, 0
	s_addc_u32 s48, s29, 0
	s_mov_b32 s49, -2
	s_waitcnt lgkmcnt(0)
	v_mov_b32_e32 v1, v0
	v_mov_b64_e32 v[2:3], 0
	v_mov_b64_e32 v[4:5], 0
	v_mov_b64_e32 v[6:7], 0
	v_mov_b64_e32 v[16:17], 0
	v_mov_b64_e32 v[18:19], 0
	v_mov_b64_e32 v[20:21], 0
	v_mov_b64_e32 v[22:23], 0
	v_mov_b64_e32 v[32:33], 0
	v_mov_b64_e32 v[34:35], 0
	v_mov_b64_e32 v[36:37], 0
	v_mov_b64_e32 v[38:39], 0
	v_mov_b64_e32 v[48:49], 0
	v_mov_b64_e32 v[50:51], 0
	v_mov_b64_e32 v[52:53], 0
	v_mov_b64_e32 v[54:55], 0
	v_mov_b64_e32 v[8:9], 0
	v_mov_b64_e32 v[10:11], 0
	v_mov_b64_e32 v[12:13], 0
	v_mov_b64_e32 v[14:15], 0
	v_mov_b64_e32 v[24:25], 0
	v_mov_b64_e32 v[26:27], 0
	v_mov_b64_e32 v[28:29], 0
	v_mov_b64_e32 v[30:31], 0
	v_mov_b64_e32 v[40:41], 0
	v_mov_b64_e32 v[42:43], 0
	v_mov_b64_e32 v[44:45], 0
	v_mov_b64_e32 v[46:47], 0
	v_mov_b64_e32 v[56:57], 0
	v_mov_b64_e32 v[58:59], 0
	v_mov_b64_e32 v[60:61], 0
	v_mov_b64_e32 v[62:63], 0
	v_mov_b64_e32 v[64:65], 0
	v_mov_b64_e32 v[66:67], 0
	v_mov_b64_e32 v[68:69], 0
	v_mov_b64_e32 v[70:71], 0
	v_mov_b64_e32 v[80:81], 0
	v_mov_b64_e32 v[82:83], 0
	v_mov_b64_e32 v[84:85], 0
	v_mov_b64_e32 v[86:87], 0
	v_mov_b64_e32 v[96:97], 0
	v_mov_b64_e32 v[98:99], 0
	v_mov_b64_e32 v[100:101], 0
	v_mov_b64_e32 v[102:103], 0
	v_mov_b64_e32 v[112:113], 0
	v_mov_b64_e32 v[114:115], 0
	v_mov_b64_e32 v[116:117], 0
	v_mov_b64_e32 v[118:119], 0
	v_mov_b64_e32 v[72:73], 0
	v_mov_b64_e32 v[74:75], 0
	v_mov_b64_e32 v[76:77], 0
	v_mov_b64_e32 v[78:79], 0
	v_mov_b64_e32 v[88:89], 0
	v_mov_b64_e32 v[90:91], 0
	v_mov_b64_e32 v[92:93], 0
	v_mov_b64_e32 v[94:95], 0
	v_mov_b64_e32 v[104:105], 0
	v_mov_b64_e32 v[106:107], 0
	v_mov_b64_e32 v[108:109], 0
	v_mov_b64_e32 v[110:111], 0
	v_mov_b64_e32 v[120:121], 0
	v_mov_b64_e32 v[122:123], 0
	v_mov_b64_e32 v[124:125], 0
	v_mov_b64_e32 v[126:127], 0
	v_xor_b32_e32 v144, 64, v149
	v_xor_b32_e32 v145, 64, v150
	v_xor_b32_e32 v216, 64, v151
	v_add_u32_e32 v217, 0x18000, v147
	v_xor_b32_e32 v234, 64, v217
	v_add_u32_e32 v235, 0x1c000, v147
	v_xor_b32_e32 v252, 64, v235
	s_waitcnt vmcnt(0)
	s_cmpk_lt_u32 s3, 0x100
	s_cbranch_scc1 .Lst_in_s5
	s_barrier

.LBB0_759:
	s_ashr_i32 s15, s14, 31
	v_cmp_lt_i64_e32 vcc, s[16:17], v[136:137]
	s_lshl_b64 s[16:17], s[14:15], 21
	s_add_u32 s16, s96, s16
	s_addc_u32 s17, s97, s17
	s_and_b64 s[18:19], vcc, exec
	s_cselect_b32 s1, s17, s21
	s_cselect_b32 s9, s16, s20
	s_ashr_i32 s13, s12, 31
	s_lshl_b64 s[18:19], s[12:13], 20
	s_add_u32 s18, s26, s18
	s_addc_u32 s19, s27, s19
	s_and_b64 s[24:25], vcc, exec
	s_cselect_b32 s13, s19, s23
	s_cselect_b32 s15, s18, s22
	s_add_u32 s20, s20, 0x100080
	s_addc_u32 s21, s21, 0
	s_add_u32 s43, s22, 0x100
	v_mov_b32_e32 v0, 0
	s_addc_u32 s44, s23, 0
	s_mov_b32 s45, -2
	s_waitcnt lgkmcnt(0)
	v_mov_b32_e32 v1, v0
	v_mov_b64_e32 v[2:3], 0
	v_mov_b64_e32 v[4:5], 0
	v_mov_b64_e32 v[6:7], 0
	v_mov_b64_e32 v[16:17], 0
	v_mov_b64_e32 v[18:19], 0
	v_mov_b64_e32 v[20:21], 0
	v_mov_b64_e32 v[22:23], 0
	v_mov_b64_e32 v[32:33], 0
	v_mov_b64_e32 v[34:35], 0
	v_mov_b64_e32 v[36:37], 0
	v_mov_b64_e32 v[38:39], 0
	v_mov_b64_e32 v[48:49], 0
	v_mov_b64_e32 v[50:51], 0
	v_mov_b64_e32 v[52:53], 0
	v_mov_b64_e32 v[54:55], 0
	v_mov_b64_e32 v[8:9], 0
	v_mov_b64_e32 v[10:11], 0
	v_mov_b64_e32 v[12:13], 0
	v_mov_b64_e32 v[14:15], 0
	v_mov_b64_e32 v[24:25], 0
	v_mov_b64_e32 v[26:27], 0
	v_mov_b64_e32 v[28:29], 0
	v_mov_b64_e32 v[30:31], 0
	v_mov_b64_e32 v[40:41], 0
	v_mov_b64_e32 v[42:43], 0
	v_mov_b64_e32 v[44:45], 0
	v_mov_b64_e32 v[46:47], 0
	v_mov_b64_e32 v[56:57], 0
	v_mov_b64_e32 v[58:59], 0
	v_mov_b64_e32 v[60:61], 0
	v_mov_b64_e32 v[62:63], 0
	v_mov_b64_e32 v[64:65], 0
	v_mov_b64_e32 v[66:67], 0
	v_mov_b64_e32 v[68:69], 0
	v_mov_b64_e32 v[70:71], 0
	v_mov_b64_e32 v[80:81], 0
	v_mov_b64_e32 v[82:83], 0
	v_mov_b64_e32 v[84:85], 0
	v_mov_b64_e32 v[86:87], 0
	v_mov_b64_e32 v[96:97], 0
	v_mov_b64_e32 v[98:99], 0
	v_mov_b64_e32 v[100:101], 0
	v_mov_b64_e32 v[102:103], 0
	v_mov_b64_e32 v[112:113], 0
	v_mov_b64_e32 v[114:115], 0
	v_mov_b64_e32 v[116:117], 0
	v_mov_b64_e32 v[118:119], 0
	v_mov_b64_e32 v[72:73], 0
	v_mov_b64_e32 v[74:75], 0
	v_mov_b64_e32 v[76:77], 0
	v_mov_b64_e32 v[78:79], 0
	v_mov_b64_e32 v[88:89], 0
	v_mov_b64_e32 v[90:91], 0
	v_mov_b64_e32 v[92:93], 0
	v_mov_b64_e32 v[94:95], 0
	v_mov_b64_e32 v[104:105], 0
	v_mov_b64_e32 v[106:107], 0
	v_mov_b64_e32 v[108:109], 0
	v_mov_b64_e32 v[110:111], 0
	v_mov_b64_e32 v[120:121], 0
	v_mov_b64_e32 v[122:123], 0
	v_mov_b64_e32 v[124:125], 0
	v_mov_b64_e32 v[126:127], 0
	v_xor_b32_e32 v216, 64, v145
	v_xor_b32_e32 v217, 64, v146
	v_xor_b32_e32 v234, 64, v147
	v_add_u32_e32 v235, 0x18000, v144
	v_xor_b32_e32 v244, 64, v235
	s_waitcnt vmcnt(0)
	s_cmpk_lt_u32 s3, 0x100
	s_cbranch_scc1 .Lst_in_s7
	s_barrier

.LBB0_839:
	s_ashr_i32 s37, s36, 31
	v_cmp_lt_i64_e32 vcc, s[12:13], v[184:185]
	s_lshl_b64 s[12:13], s[36:37], 20
	s_add_u32 s38, s80, s12
	s_addc_u32 s39, s81, s13
	s_and_b64 s[12:13], vcc, exec
	s_cselect_b32 s33, s39, s9
	s_cselect_b32 s37, s38, s8
	s_ashr_i32 s35, s34, 31
	s_lshl_b64 s[12:13], s[34:35], 19
	s_add_u32 s40, s44, s12
	s_addc_u32 s41, s45, s13
	s_and_b64 s[12:13], vcc, exec
	s_cselect_b32 s35, s41, s11
	s_cselect_b32 s64, s40, s10
	s_add_u32 s65, s10, 0x100
	v_mov_b32_e32 v0, 0
	s_addc_u32 s66, s11, 0
	s_mov_b32 s67, -2
	v_mov_b32_e32 v1, v0
	v_mov_b64_e32 v[2:3], 0
	v_mov_b64_e32 v[64:65], 0
	v_mov_b64_e32 v[66:67], 0
	v_mov_b64_e32 v[8:9], 0
	v_mov_b64_e32 v[10:11], 0
	v_mov_b64_e32 v[68:69], 0
	v_mov_b64_e32 v[70:71], 0
	v_mov_b64_e32 v[12:13], 0
	v_mov_b64_e32 v[14:15], 0
	v_mov_b64_e32 v[110:111], 0
	v_mov_b64_e32 v[112:113], 0
	v_mov_b64_e32 v[16:17], 0
	v_mov_b64_e32 v[18:19], 0
	v_mov_b64_e32 v[118:119], 0
	v_mov_b64_e32 v[120:121], 0
	v_mov_b64_e32 v[4:5], 0
	v_mov_b64_e32 v[6:7], 0
	v_mov_b64_e32 v[72:73], 0
	v_mov_b64_e32 v[74:75], 0
	v_mov_b64_e32 v[20:21], 0
	v_mov_b64_e32 v[22:23], 0
	v_mov_b64_e32 v[114:115], 0
	v_mov_b64_e32 v[116:117], 0
	v_mov_b64_e32 v[24:25], 0
	v_mov_b64_e32 v[26:27], 0
	v_mov_b64_e32 v[122:123], 0
	v_mov_b64_e32 v[124:125], 0
	v_mov_b64_e32 v[28:29], 0
	v_mov_b64_e32 v[30:31], 0
	v_mov_b64_e32 v[126:127], 0
	v_mov_b64_e32 v[128:129], 0
	v_mov_b64_e32 v[32:33], 0
	v_mov_b64_e32 v[34:35], 0
	v_mov_b64_e32 v[130:131], 0
	v_mov_b64_e32 v[132:133], 0
	v_mov_b64_e32 v[36:37], 0
	v_mov_b64_e32 v[38:39], 0
	v_mov_b64_e32 v[134:135], 0
	v_mov_b64_e32 v[136:137], 0
	v_mov_b64_e32 v[44:45], 0
	v_mov_b64_e32 v[46:47], 0
	v_mov_b64_e32 v[142:143], 0
	v_mov_b64_e32 v[144:145], 0
	v_mov_b64_e32 v[56:57], 0
	v_mov_b64_e32 v[58:59], 0
	v_mov_b64_e32 v[154:155], 0
	v_mov_b64_e32 v[156:157], 0
	v_mov_b64_e32 v[40:41], 0
	v_mov_b64_e32 v[42:43], 0
	v_mov_b64_e32 v[138:139], 0
	v_mov_b64_e32 v[140:141], 0
	v_mov_b64_e32 v[48:49], 0
	v_mov_b64_e32 v[50:51], 0
	v_mov_b64_e32 v[146:147], 0
	v_mov_b64_e32 v[148:149], 0
	v_mov_b64_e32 v[52:53], 0
	v_mov_b64_e32 v[54:55], 0
	v_mov_b64_e32 v[150:151], 0
	v_mov_b64_e32 v[152:153], 0
	v_mov_b64_e32 v[60:61], 0
	v_mov_b64_e32 v[62:63], 0
	v_mov_b64_e32 v[158:159], 0
	v_mov_b64_e32 v[160:161], 0
	v_xor_b32_e32 v220, 64, v171
	v_xor_b32_e32 v221, 64, v173
	v_xor_b32_e32 v238, 64, v175
	v_add_u32_e32 v239, 0x18000, v169
	v_xor_b32_e32 v240, 64, v239
	v_add_u32_e32 v241, 0x1c000, v169
	v_xor_b32_e32 v242, 64, v241
	s_waitcnt vmcnt(0)
	s_cmpk_lt_u32 s3, 0x100
	s_cbranch_scc1 .Lst_in_s8
	s_barrier

.LBB0_984:
	s_add_u32 s0, s0, 0x160080
	s_addc_u32 s1, s1, 0
	s_add_u32 s39, s14, 0x100
	v_mov_b32_e32 v0, 0
	s_addc_u32 s40, s15, 0
	s_mov_b32 s41, -2
	s_waitcnt lgkmcnt(0)
	v_mov_b32_e32 v1, v0
	v_mov_b64_e32 v[2:3], 0
	v_mov_b64_e32 v[4:5], 0
	v_mov_b64_e32 v[6:7], 0
	v_mov_b64_e32 v[16:17], 0
	v_mov_b64_e32 v[18:19], 0
	v_mov_b64_e32 v[20:21], 0
	v_mov_b64_e32 v[22:23], 0
	v_mov_b64_e32 v[32:33], 0
	v_mov_b64_e32 v[34:35], 0
	v_mov_b64_e32 v[36:37], 0
	v_mov_b64_e32 v[38:39], 0
	v_mov_b64_e32 v[48:49], 0
	v_mov_b64_e32 v[50:51], 0
	v_mov_b64_e32 v[52:53], 0
	v_mov_b64_e32 v[54:55], 0
	v_mov_b64_e32 v[8:9], 0
	v_mov_b64_e32 v[10:11], 0
	v_mov_b64_e32 v[12:13], 0
	v_mov_b64_e32 v[14:15], 0
	v_mov_b64_e32 v[24:25], 0
	v_mov_b64_e32 v[26:27], 0
	v_mov_b64_e32 v[28:29], 0
	v_mov_b64_e32 v[30:31], 0
	v_mov_b64_e32 v[40:41], 0
	v_mov_b64_e32 v[42:43], 0
	v_mov_b64_e32 v[44:45], 0
	v_mov_b64_e32 v[46:47], 0
	v_mov_b64_e32 v[56:57], 0
	v_mov_b64_e32 v[58:59], 0
	v_mov_b64_e32 v[60:61], 0
	v_mov_b64_e32 v[62:63], 0
	v_mov_b64_e32 v[64:65], 0
	v_mov_b64_e32 v[66:67], 0
	v_mov_b64_e32 v[68:69], 0
	v_mov_b64_e32 v[70:71], 0
	v_mov_b64_e32 v[80:81], 0
	v_mov_b64_e32 v[82:83], 0
	v_mov_b64_e32 v[84:85], 0
	v_mov_b64_e32 v[86:87], 0
	v_mov_b64_e32 v[96:97], 0
	v_mov_b64_e32 v[98:99], 0
	v_mov_b64_e32 v[100:101], 0
	v_mov_b64_e32 v[102:103], 0
	v_mov_b64_e32 v[112:113], 0
	v_mov_b64_e32 v[114:115], 0
	v_mov_b64_e32 v[116:117], 0
	v_mov_b64_e32 v[118:119], 0
	v_mov_b64_e32 v[72:73], 0
	v_mov_b64_e32 v[74:75], 0
	v_mov_b64_e32 v[76:77], 0
	v_mov_b64_e32 v[78:79], 0
	v_mov_b64_e32 v[88:89], 0
	v_mov_b64_e32 v[90:91], 0
	v_mov_b64_e32 v[92:93], 0
	v_mov_b64_e32 v[94:95], 0
	v_mov_b64_e32 v[104:105], 0
	v_mov_b64_e32 v[106:107], 0
	v_mov_b64_e32 v[108:109], 0
	v_mov_b64_e32 v[110:111], 0
	v_mov_b64_e32 v[120:121], 0
	v_mov_b64_e32 v[122:123], 0
	v_mov_b64_e32 v[124:125], 0
	v_mov_b64_e32 v[126:127], 0
	v_xor_b32_e32 v216, 64, v141
	v_xor_b32_e32 v217, 64, v142
	v_xor_b32_e32 v218, 64, v143
	v_add_u32_e32 v219, 0x18000, v140
	v_xor_b32_e32 v220, 64, v219
	s_waitcnt vmcnt(0)
	s_cmpk_lt_u32 s3, 0x100
	s_cbranch_scc1 .Lst_in_s9
	s_barrier
